# wave sums of the row passes and LayerNorms: ds_swizzle butterfly steps replaced by DPP moves and v_permlane16_swap (same butterfly, no LDS round trips), on top of the barrier without per-XCD relay
# baseline (speedup 1.0000x reference)
; __device__ __forceinline__ float bf_lo(unsigned w) { return __uint_as_float(w << 16); }
; __device__ __forceinline__ float wave_sum(float v) {
;     v += __int_as_float(__builtin_amdgcn_ds_swizzle(__float_as_int(v), 0x041F));
;     v += __int_as_float(__builtin_amdgcn_ds_swizzle(__float_as_int(v), 0x081F));
;     v += __int_as_float(__builtin_amdgcn_ds_swizzle(__float_as_int(v), 0x101F));
;     v += __int_as_float(__builtin_amdgcn_ds_swizzle(__float_as_int(v), 0x201F));
;     v += __int_as_float(__builtin_amdgcn_ds_swizzle(__float_as_int(v), 0x401F));
;     auto rr = __builtin_amdgcn_permlane32_swap(__float_as_uint(v), __float_as_uint(v), false, false);
;     return __uint_as_float(rr[0]) + __uint_as_float(rr[1]);
; __global__ void __launch_bounds__(512, 2) hse_fwd(Params P) {
;     ...
;                     { const u32x4 w = R.wcq; float ss = bf_lo(w.x) * bf_lo(w.x) + bf_hi(w.x) * bf_hi(w.x) + bf_lo(w.y) * bf_lo(w.y) + bf_hi(w.y) * bf_hi(w.y)
;                           + bf_lo(w.z) * bf_lo(w.z) + bf_hi(w.z) * bf_hi(w.z) + bf_lo(w.w) * bf_lo(w.w) + bf_hi(w.w) * bf_hi(w.w);
;                       ss = wave_sum(ss); if (lane == 0) sqv[ar] = rsqrtf(ss * (1.0f / 512.0f) + EPS); }
;                     { const u32x2 w = R.wkv; const float x0 = bf_lo(w.x), x1 = bf_hi(w.x), x2 = bf_lo(w.y), x3 = bf_hi(w.y);
;                       float ss = wave_sum(x0 * x0 + x1 * x1 + x2 * x2 + x3 * x3); const float rs = rsqrtf(ss * (1.0f / 256.0f) + EPS);
;                       const f32x4 y = {x0 * rs * gk[0], x1 * rs * gk[1], x2 * rs * gk[2], x3 * rs * gk[3]};
;                       float* o = isp ? out + O_CKV_P + ((size_t)l * MP + ar) * 256 : out + O_CKV_S + ((size_t)l * MS + (ar - MP)) * 256; *(f32x4*)(o + lane * 4) = y;
;                       *(u32x2*)(ckva + (size_t)kvr * 256 + lane * 4) = (u32x2){cvt_pk_bf16(y[0], y[1]), cvt_pk_bf16(y[2], y[3])}; }
;                     if (lane < 32) { const float x1 = bf_lo(R.wkr), x2 = bf_hi(R.wkr);
;                       const float o1 = x1 * R.csr.x - x2 * R.csr.y, o2 = x2 * R.csr.x + x1 * R.csr.y;
;                       float* o = isp ? out + O_KR_P + ((size_t)l * MP + ar) * 64 : out + O_KR_S + ((size_t)l * MS + (ar - MP)) * 64; o[lane] = o1; o[32 + lane] = o2;
;                       *(unsigned*)(kropa + (size_t)kvr * 64 + 2 * lane) = cvt_pk_bf16(o1, o2); }
.LBB0_4449:
	s_waitcnt vmcnt(11)
	v_lshlrev_b32_e32 v79, 16, v74
	v_and_b32_e32 v74, 0xffff0000, v74
	v_mul_f32_e32 v74, v74, v74
	v_fmac_f32_e32 v74, v79, v79
	v_lshlrev_b32_e32 v79, 16, v75
	v_fmac_f32_e32 v74, v79, v79
	v_and_b32_e32 v75, 0xffff0000, v75
	v_fmac_f32_e32 v74, v75, v75
	v_lshlrev_b32_e32 v75, 16, v76
	v_fmac_f32_e32 v74, v75, v75
	v_and_b32_e32 v75, 0xffff0000, v76
	v_fmac_f32_e32 v74, v75, v75
	v_lshlrev_b32_e32 v75, 16, v77
	v_fmac_f32_e32 v74, v75, v75
	v_and_b32_e32 v75, 0xffff0000, v77
	v_fmac_f32_e32 v74, v75, v75
	s_nop 1
	v_mov_b32_dpp v75, v74 quad_perm:[1,0,3,2] row_mask:0xf bank_mask:0xf
	s_waitcnt lgkmcnt(0)
	v_add_f32_e32 v74, v74, v75
	s_nop 1
	v_mov_b32_dpp v75, v74 quad_perm:[2,3,0,1] row_mask:0xf bank_mask:0xf
	s_waitcnt lgkmcnt(0)
	v_add_f32_e32 v74, v74, v75
	s_nop 1
	v_mov_b32_dpp v75, v74 row_half_mirror row_mask:0xf bank_mask:0xf
	s_waitcnt lgkmcnt(0)
	v_add_f32_e32 v74, v74, v75
	s_nop 1
	v_mov_b32_dpp v75, v74 row_mirror row_mask:0xf bank_mask:0xf
	s_waitcnt lgkmcnt(0)
	v_add_f32_e32 v74, v74, v75
	v_mov_b32_e32 v75, v74
	s_nop 1
	v_permlane16_swap_b32_e32 v74, v75
	s_waitcnt lgkmcnt(0)
	v_add_f32_e32 v74, v74, v75
	v_mov_b32_e32 v75, v74
	s_nop 1
	v_permlane32_swap_b32_e32 v74, v75
	s_and_saveexec_b64 s[14:15], s[4:5]
	s_xor_b64 s[14:15], exec, s[14:15]
	s_ashr_i32 s31, s30, 31
	s_or_saveexec_b64 s[28:29], s[14:15]
	v_mov_b64_e32 v[110:111], s[30:31]
	s_xor_b64 exec, exec, s[28:29]
	s_cbranch_execz .LBB0_4453
	v_add_f32_e32 v74, v74, v75
	v_mov_b32_e32 v75, 0x3727c5ac
	v_fmamk_f32 v74, v74, 0x3b000000, v75
	s_mov_b32 s14, 0x800000
	v_cmp_gt_f32_e32 vcc, s14, v74
	v_mul_f32_e32 v75, 0x4b800000, v74
	s_ashr_i32 s31, s30, 31
	v_cndmask_b32_e32 v74, v74, v75, vcc
	v_rsq_f32_e32 v74, v74
	s_lshl_b64 s[14:15], s[30:31], 2
	s_add_u32 s14, s45, s14
	s_addc_u32 s15, s46, s15
	v_mul_f32_e32 v75, 0x45800000, v74
	v_cndmask_b32_e32 v74, v74, v75, vcc
	v_mov_b64_e32 v[110:111], s[30:31]
	global_store_dword v32, v74, s[14:15]
.LBB0_4453:
	s_or_b64 exec, exec, s[28:29]
	s_waitcnt vmcnt(10)
	v_lshlrev_b32_e32 v74, 16, v108
	v_and_b32_e32 v75, 0xffff0000, v108
	v_pk_mul_f32 v[76:77], v[74:75], v[74:75]
	v_lshlrev_b32_e32 v108, 16, v109
	v_and_b32_e32 v109, 0xffff0000, v109
	v_pk_mul_f32 v[114:115], v[108:109], v[108:109]
	v_add_f32_e32 v76, v76, v77
	v_add_f32_e32 v76, v114, v76
	v_add_f32_e32 v76, v115, v76
	s_nop 1
	v_mov_b32_dpp v77, v76 quad_perm:[1,0,3,2] row_mask:0xf bank_mask:0xf
	v_readlane_b32 s14, v253, 29
	s_sub_i32 s28, s34, s14
	s_mov_b32 s14, 0x800000
	s_add_i32 s26, s30, 0xffff8000
	s_waitcnt lgkmcnt(0)
	v_add_f32_e32 v76, v76, v77
	s_nop 1
	v_mov_b32_dpp v77, v76 quad_perm:[2,3,0,1] row_mask:0xf bank_mask:0xf
	v_readlane_b32 s34, v253, 23
	v_readlane_b32 s35, v253, 24
	v_mov_b32_e32 v79, s26
	s_waitcnt lgkmcnt(0)
	v_add_f32_e32 v76, v76, v77
	s_nop 1
	v_mov_b32_dpp v77, v76 row_half_mirror row_mask:0xf bank_mask:0xf
	s_waitcnt lgkmcnt(0)
	v_add_f32_e32 v76, v76, v77
	s_nop 1
	v_mov_b32_dpp v77, v76 row_mirror row_mask:0xf bank_mask:0xf
	s_waitcnt lgkmcnt(0)
	v_add_f32_e32 v76, v76, v77
	v_mov_b32_e32 v77, v76
	s_nop 1
	v_permlane16_swap_b32_e32 v76, v77
	s_waitcnt lgkmcnt(0)
	v_add_f32_e32 v76, v76, v77
	v_mov_b32_e32 v77, v76
	s_nop 1
	v_permlane32_swap_b32_e32 v76, v77
	v_add_f32_e32 v76, v76, v77
	v_mov_b32_e32 v77, 0x3727c5ac
	v_fmamk_f32 v76, v76, 0x3b800000, v77
	v_cmp_gt_f32_e32 vcc, s14, v76
	v_mul_f32_e32 v77, 0x4b800000, v76
	s_and_b64 s[14:15], s[6:7], exec
	v_cndmask_b32_e32 v76, v76, v77, vcc
	s_mov_b32 s14, 0x17658000
	v_rsq_f32_e32 v76, v76
	s_cselect_b32 s14, s14, 0x10400000
	s_add_u32 s29, s42, s14
	s_addc_u32 s31, s41, 0
	s_and_b64 s[14:15], s[6:7], exec
	v_mul_f32_e32 v77, 0x45800000, v76
	s_cselect_b32 s14, 19, 25
	v_cndmask_b32_e32 v76, v76, v77, vcc
	s_lshl_b64 s[14:15], s[34:35], s14
	v_pk_mul_f32 v[74:75], v[76:77], v[74:75] op_sel_hi:[0,1]
	v_pk_mul_f32 v[76:77], v[76:77], v[108:109] op_sel_hi:[0,1]
	v_cndmask_b32_e64 v109, v111, 0, s[6:7]
	v_cndmask_b32_e64 v108, v110, v79, s[6:7]
	s_add_u32 s38, s29, s14
	s_addc_u32 s39, s31, s15
	v_lshlrev_b64 v[110:111], 10, v[108:109]
	v_lshl_add_u64 v[110:111], s[38:39], 0, v[110:111]
	v_mov_b32_e32 v79, v32
	s_ashr_i32 s29, s28, 31
	v_pk_mul_f32 v[74:75], v[0:1], v[74:75]
	v_pk_mul_f32 v[76:77], v[2:3], v[76:77]
	v_lshl_add_u64 v[110:111], v[110:111], 0, v[78:79]
	s_lshl_b64 s[14:15], s[28:29], 9
	global_store_dwordx4 v[110:111], v[74:77], off
	s_nop 1
	v_cvt_pk_bf16_f32 v74, v74, v75
	v_cvt_pk_bf16_f32 v75, v76, v77
	v_lshl_add_u64 v[76:77], v[88:89], 0, s[14:15]
	global_store_dwordx2 v[76:77], v[74:75], off
	s_and_saveexec_b64 s[34:35], s[0:1]
	s_cbranch_execz .LBB0_4455
	s_and_b64 s[14:15], s[6:7], exec
	s_mov_b32 s14, 0x17758000
	s_cselect_b32 s14, s14, 0x14400000
	s_add_u32 s31, s42, s14
	s_addc_u32 s38, s41, 0
	s_and_b64 s[14:15], s[6:7], exec
	v_readlane_b32 s62, v253, 23
	s_cselect_b32 s14, 17, 23
	v_readlane_b32 s63, v253, 24
	v_lshlrev_b32_e32 v74, 16, v113
	v_and_b32_e32 v75, 0xffff0000, v113
	s_lshl_b64 s[14:15], s[62:63], s14
	v_pk_mul_f32 v[76:77], v[106:107], v[74:75]
	v_pk_mul_f32 v[74:75], v[106:107], v[74:75] op_sel:[0,1] op_sel_hi:[1,0]
	s_add_u32 s14, s31, s14
	v_add_f32_e32 v99, v74, v75
	s_addc_u32 s15, s38, s15
	v_lshlrev_b64 v[74:75], 8, v[108:109]
	v_sub_f32_e32 v79, v76, v77
	v_lshl_add_u64 v[74:75], s[14:15], 0, v[74:75]
	v_lshlrev_b32_e32 v76, 2, v80
	v_mov_b32_e32 v77, v32
	v_lshl_add_u64 v[74:75], v[74:75], 0, v[76:77]
	s_lshl_b64 s[14:15], s[28:29], 7
	global_store_dword v[74:75], v79, off
	global_store_dword v[74:75], v99, off offset:128
	v_lshl_add_u64 v[74:75], v[90:91], 0, s[14:15]
	v_cvt_pk_bf16_f32 v76, v79, v99
	global_store_dword v[74:75], v76, off

; __device__ __forceinline__ float bf_lo(unsigned w) { return __uint_as_float(w << 16); }
; __device__ __forceinline__ float wave_sum(float v) {
;     v += __int_as_float(__builtin_amdgcn_ds_swizzle(__float_as_int(v), 0x041F));
;     v += __int_as_float(__builtin_amdgcn_ds_swizzle(__float_as_int(v), 0x081F));
;     v += __int_as_float(__builtin_amdgcn_ds_swizzle(__float_as_int(v), 0x101F));
;     v += __int_as_float(__builtin_amdgcn_ds_swizzle(__float_as_int(v), 0x201F));
;     v += __int_as_float(__builtin_amdgcn_ds_swizzle(__float_as_int(v), 0x401F));
;     auto rr = __builtin_amdgcn_permlane32_swap(__float_as_uint(v), __float_as_uint(v), false, false);
;     return __uint_as_float(rr[0]) + __uint_as_float(rr[1]);
; __global__ void __launch_bounds__(512, 2) hse_fwd(Params P) {
;     ...
;                     { const u32x4 w = R.wcq; float ss = bf_lo(w.x) * bf_lo(w.x) + bf_hi(w.x) * bf_hi(w.x) + bf_lo(w.y) * bf_lo(w.y) + bf_hi(w.y) * bf_hi(w.y)
;                           + bf_lo(w.z) * bf_lo(w.z) + bf_hi(w.z) * bf_hi(w.z) + bf_lo(w.w) * bf_lo(w.w) + bf_hi(w.w) * bf_hi(w.w);
;                       ss = wave_sum(ss); if (lane == 0) sqv[ar] = rsqrtf(ss * (1.0f / 512.0f) + EPS); }
;                     { const u32x2 w = R.wkv; const float x0 = bf_lo(w.x), x1 = bf_hi(w.x), x2 = bf_lo(w.y), x3 = bf_hi(w.y);
;                       float ss = wave_sum(x0 * x0 + x1 * x1 + x2 * x2 + x3 * x3); const float rs = rsqrtf(ss * (1.0f / 256.0f) + EPS);
;                       const f32x4 y = {x0 * rs * gk[0], x1 * rs * gk[1], x2 * rs * gk[2], x3 * rs * gk[3]};
;                       float* o = isp ? out + O_CKV_P + ((size_t)l * MP + ar) * 256 : out + O_CKV_S + ((size_t)l * MS + (ar - MP)) * 256; *(f32x4*)(o + lane * 4) = y;
;                       *(u32x2*)(ckva + (size_t)kvr * 256 + lane * 4) = (u32x2){cvt_pk_bf16(y[0], y[1]), cvt_pk_bf16(y[2], y[3])}; }
;                     if (lane < 32) { const float x1 = bf_lo(R.wkr), x2 = bf_hi(R.wkr);
;                       const float o1 = x1 * R.csr.x - x2 * R.csr.y, o2 = x2 * R.csr.x + x1 * R.csr.y;
;                       float* o = isp ? out + O_KR_P + ((size_t)l * MP + ar) * 64 : out + O_KR_S + ((size_t)l * MS + (ar - MP)) * 64; o[lane] = o1; o[32 + lane] = o2;
;                       *(unsigned*)(kropa + (size_t)kvr * 64 + 2 * lane) = cvt_pk_bf16(o1, o2); }
.LBB0_4482:
	s_waitcnt vmcnt(9)
	v_lshlrev_b32_e32 v42, 16, v38
	v_and_b32_e32 v38, 0xffff0000, v38
	v_mul_f32_e32 v38, v38, v38
	v_fmac_f32_e32 v38, v42, v42
	v_lshlrev_b32_e32 v42, 16, v39
	v_fmac_f32_e32 v38, v42, v42
	v_and_b32_e32 v39, 0xffff0000, v39
	v_fmac_f32_e32 v38, v39, v39
	v_lshlrev_b32_e32 v39, 16, v40
	v_fmac_f32_e32 v38, v39, v39
	v_and_b32_e32 v39, 0xffff0000, v40
	v_fmac_f32_e32 v38, v39, v39
	v_lshlrev_b32_e32 v39, 16, v41
	v_fmac_f32_e32 v38, v39, v39
	v_and_b32_e32 v39, 0xffff0000, v41
	v_fmac_f32_e32 v38, v39, v39
	s_nop 1
	v_mov_b32_dpp v39, v38 quad_perm:[1,0,3,2] row_mask:0xf bank_mask:0xf
	s_waitcnt lgkmcnt(0)
	v_add_f32_e32 v38, v38, v39
	s_nop 1
	v_mov_b32_dpp v39, v38 quad_perm:[2,3,0,1] row_mask:0xf bank_mask:0xf
	s_waitcnt lgkmcnt(0)
	v_add_f32_e32 v38, v38, v39
	s_nop 1
	v_mov_b32_dpp v39, v38 row_half_mirror row_mask:0xf bank_mask:0xf
	s_waitcnt lgkmcnt(0)
	v_add_f32_e32 v38, v38, v39
	s_nop 1
	v_mov_b32_dpp v39, v38 row_mirror row_mask:0xf bank_mask:0xf
	s_waitcnt lgkmcnt(0)
	v_add_f32_e32 v38, v38, v39
	v_mov_b32_e32 v39, v38
	s_nop 1
	v_permlane16_swap_b32_e32 v38, v39
	s_waitcnt lgkmcnt(0)
	v_add_f32_e32 v40, v38, v39
	v_mov_b32_e32 v41, v40
	s_nop 1
	v_permlane32_swap_b32_e32 v40, v41
	s_and_saveexec_b64 s[6:7], s[4:5]
	s_xor_b64 s[6:7], exec, s[6:7]
	s_ashr_i32 s31, s30, 31
	s_or_saveexec_b64 s[6:7], s[6:7]
	v_mov_b64_e32 v[38:39], s[30:31]
	s_xor_b64 exec, exec, s[6:7]
	s_cbranch_execz .LBB0_4486
	v_add_f32_e32 v38, v40, v41
	v_mov_b32_e32 v39, 0x3727c5ac
	v_fmamk_f32 v38, v38, 0x3b000000, v39
	s_mov_b32 s15, 0x800000
	v_cmp_gt_f32_e32 vcc, s15, v38
	v_mul_f32_e32 v39, 0x4b800000, v38
	s_ashr_i32 s31, s30, 31
	v_cndmask_b32_e32 v38, v38, v39, vcc
	v_rsq_f32_e32 v38, v38
	s_lshl_b64 s[28:29], s[30:31], 2
	s_add_u32 s28, s45, s28
	s_addc_u32 s29, s46, s29
	v_mul_f32_e32 v39, 0x45800000, v38
	v_cndmask_b32_e32 v38, v38, v39, vcc
	global_store_dword v32, v38, s[28:29]
	v_mov_b64_e32 v[38:39], s[30:31]
.LBB0_4486:
	s_or_b64 exec, exec, s[6:7]
	s_waitcnt vmcnt(8)
	v_lshlrev_b32_e32 v40, 16, v102
	v_and_b32_e32 v41, 0xffff0000, v102
	v_pk_mul_f32 v[42:43], v[40:41], v[40:41]
	v_lshlrev_b32_e32 v44, 16, v103
	v_and_b32_e32 v45, 0xffff0000, v103
	v_pk_mul_f32 v[46:47], v[44:45], v[44:45]
	v_add_f32_e32 v42, v42, v43
	v_add_f32_e32 v42, v46, v42
	v_add_f32_e32 v42, v47, v42
	s_nop 1
	v_mov_b32_dpp v43, v42 quad_perm:[1,0,3,2] row_mask:0xf bank_mask:0xf
	v_readlane_b32 s6, v253, 29
	s_sub_i32 s36, s14, s6
	s_mov_b32 s14, 0x800000
	s_cmp_lt_i32 s30, 0x8000
	s_waitcnt lgkmcnt(0)
	v_add_f32_e32 v42, v42, v43
	s_nop 1
	v_mov_b32_dpp v43, v42 quad_perm:[2,3,0,1] row_mask:0xf bank_mask:0xf
	s_cselect_b64 s[28:29], -1, 0
	s_add_i32 s26, s30, 0xffff8000
	s_cmpk_gt_i32 s30, 0x7fff
	s_cselect_b64 s[6:7], -1, 0
	s_waitcnt lgkmcnt(0)
	v_add_f32_e32 v42, v42, v43
	s_nop 1
	v_mov_b32_dpp v43, v42 row_half_mirror row_mask:0xf bank_mask:0xf
	v_readlane_b32 s60, v253, 23
	v_readlane_b32 s61, v253, 24
	v_cndmask_b32_e64 v39, v39, 0, s[6:7]
	v_mov_b32_e32 v79, v32
	s_waitcnt lgkmcnt(0)
	v_add_f32_e32 v42, v42, v43
	s_nop 1
	v_mov_b32_dpp v43, v42 row_mirror row_mask:0xf bank_mask:0xf
	s_waitcnt lgkmcnt(0)
	v_add_f32_e32 v42, v42, v43
	v_mov_b32_e32 v43, v42
	s_nop 1
	v_permlane16_swap_b32_e32 v42, v43
	s_waitcnt lgkmcnt(0)
	v_add_f32_e32 v42, v42, v43
	v_mov_b32_e32 v43, v42
	s_nop 1
	v_permlane32_swap_b32_e32 v42, v43
	v_add_f32_e32 v42, v42, v43
	v_mov_b32_e32 v43, 0x3727c5ac
	v_fmamk_f32 v42, v42, 0x3b800000, v43
	v_cmp_gt_f32_e32 vcc, s14, v42
	v_mul_f32_e32 v43, 0x4b800000, v42
	s_and_b64 s[14:15], s[6:7], exec
	v_cndmask_b32_e32 v42, v42, v43, vcc
	v_rsq_f32_e32 v42, v42
	s_mov_b32 s14, 0x17658000
	s_cselect_b32 s14, s14, 0x10400000
	s_cselect_b32 s15, 19, 25
	v_mul_f32_e32 v43, 0x45800000, v42
	v_cndmask_b32_e32 v42, v42, v43, vcc
	s_add_u32 s31, s42, s14
	v_pk_mul_f32 v[40:41], v[42:43], v[40:41] op_sel_hi:[0,1]
	v_pk_mul_f32 v[42:43], v[42:43], v[44:45] op_sel_hi:[0,1]
	v_mov_b32_e32 v44, s26
	s_addc_u32 s34, s41, 0
	s_lshl_b64 s[14:15], s[60:61], s15
	v_cndmask_b32_e64 v38, v38, v44, s[6:7]
	s_add_u32 s14, s31, s14
	s_addc_u32 s15, s34, s15
	v_lshlrev_b64 v[44:45], 10, v[38:39]
	v_lshl_add_u64 v[44:45], s[14:15], 0, v[44:45]
	s_ashr_i32 s37, s36, 31
	v_pk_mul_f32 v[40:41], v[0:1], v[40:41]
	v_pk_mul_f32 v[42:43], v[2:3], v[42:43]
	v_lshl_add_u64 v[44:45], v[44:45], 0, v[78:79]
	s_lshl_b64 s[14:15], s[36:37], 9
	global_store_dwordx4 v[44:45], v[40:43], off
	s_nop 1
	v_cvt_pk_bf16_f32 v40, v40, v41
	v_cvt_pk_bf16_f32 v41, v42, v43
	v_lshl_add_u64 v[42:43], v[88:89], 0, s[14:15]
	global_store_dwordx2 v[42:43], v[40:41], off
	s_and_saveexec_b64 s[34:35], s[0:1]
	s_cbranch_execz .LBB0_4488
	s_and_b64 s[14:15], s[6:7], exec
	s_mov_b32 s14, 0x17758000
	s_cselect_b32 s14, s14, 0x14400000
	s_add_u32 s31, s42, s14
	s_addc_u32 s39, s41, 0
	s_and_b64 s[14:15], s[6:7], exec
	v_readlane_b32 s60, v253, 23
	s_cselect_b32 s14, 17, 23
	v_readlane_b32 s61, v253, 24
	s_lshl_b64 s[14:15], s[60:61], s14
	v_lshlrev_b32_e32 v40, 16, v112
	v_and_b32_e32 v41, 0xffff0000, v112
	s_add_u32 s14, s31, s14
	v_pk_mul_f32 v[42:43], v[100:101], v[40:41]
	v_pk_mul_f32 v[40:41], v[100:101], v[40:41] op_sel:[0,1] op_sel_hi:[1,0]
	s_addc_u32 s15, s39, s15
	v_lshlrev_b64 v[38:39], 8, v[38:39]
	v_sub_f32_e32 v42, v42, v43
	v_add_f32_e32 v43, v40, v41
	v_lshl_add_u64 v[38:39], s[14:15], 0, v[38:39]
	v_lshlrev_b32_e32 v40, 2, v80
	v_mov_b32_e32 v41, v32
	v_lshl_add_u64 v[38:39], v[38:39], 0, v[40:41]
	s_lshl_b64 s[14:15], s[36:37], 7
	global_store_dword v[38:39], v42, off
	global_store_dword v[38:39], v43, off offset:128
	v_lshl_add_u64 v[38:39], v[90:91], 0, s[14:15]
	v_cvt_pk_bf16_f32 v40, v42, v43
	global_store_dword v[38:39], v40, off

; __device__ __forceinline__ float bf_lo(unsigned w) { return __uint_as_float(w << 16); }
; __device__ __forceinline__ float bf_hi(unsigned w) { return __uint_as_float(w & 0xffff0000u); }
; #define INP(k) pt.in(k)
; __device__ __forceinline__ float wave_sum(float v) {
;     v += __int_as_float(__builtin_amdgcn_ds_swizzle(__float_as_int(v), 0x041F));
;     v += __int_as_float(__builtin_amdgcn_ds_swizzle(__float_as_int(v), 0x081F));
;     v += __int_as_float(__builtin_amdgcn_ds_swizzle(__float_as_int(v), 0x101F));
;     v += __int_as_float(__builtin_amdgcn_ds_swizzle(__float_as_int(v), 0x201F));
;     v += __int_as_float(__builtin_amdgcn_ds_swizzle(__float_as_int(v), 0x401F));
;     auto rr = __builtin_amdgcn_permlane32_swap(__float_as_uint(v), __float_as_uint(v), false, false);
;     return __uint_as_float(rr[0]) + __uint_as_float(rr[1]);
; __global__ void __launch_bounds__(512, 2) hse_fwd(Params P) {
;     ...
;         for (int ar = bid * 8 + wave; ar < MX; ar += G * 8) { bf16_t* xr = xbuf + (size_t)ar * DM; f32x4 v[8]; float s = 0.f;
;             const float* xs = ar < MP ? INP(0) + (size_t)ar * DM : INP(1) + (size_t)(ar - MP) * DM; const bf16_t* vb = hbuf + (size_t)ar * DM; const int st = row_stream(ar); const float* a = adal + (size_t)st * NADA;
; #pragma unroll
;             for (int i = 0; i < 8; ++i) { f32x4 x; if (l == 0) x = *(const f32x4*)(xs + i * 256 + lane * 4); else { const u32x2 xw = *(const u32x2*)(xr + i * 256 + lane * 4); x = (f32x4){bf_lo(xw.x), bf_hi(xw.x), bf_lo(xw.y), bf_hi(xw.y)}; }
;                 const u32x2 w = *(const u32x2*)(vb + i * 256 + lane * 4);
;                 v[i] = x * ALPHA + (f32x4){bf_lo(w.x), bf_hi(w.x), bf_lo(w.y), bf_hi(w.y)}; s += (v[i][0] + v[i][1]) + (v[i][2] + v[i][3]); }
;             if (st != cst) { cst = st;
; #pragma unroll
;                 for (int i = 0; i < 8; ++i) { const int c = i * 256 + lane * 4; sh[i] = *(const f32x4*)(a + 3 * DM + c); sc[i] = *(const f32x4*)(a + 4 * DM + c); } }
;             const float mean = wave_sum(s) * (1.0f / DM); float q = 0.f;
; #pragma unroll
;             for (int i = 0; i < 8; ++i) { const f32x4 d = v[i] - mean; q += (d[0] * d[0] + d[1] * d[1]) + (d[2] * d[2] + d[3] * d[3]); }
;             const float rstd = rsqrtf(wave_sum(q) * (1.0f / DM) + EPS);
.Lf1_x7:
	v_lshlrev_b32_e32 v132, 16, v190
	v_and_b32_e32 v133, 0xffff0000, v190
	v_lshlrev_b32_e32 v130, 16, v191
	v_and_b32_e32 v131, 0xffff0000, v191
	v_pk_fma_f32 v[130:131], v[160:161], s[0:1], v[130:131] op_sel_hi:[1,0,1]
	v_pk_fma_f32 v[132:133], v[158:159], s[0:1], v[132:133] op_sel_hi:[1,0,1]
	v_add_f32_e32 v148, v130, v131
	v_add_f32_e32 v147, v132, v133
	v_add_f32_e32 v147, v147, v148
	v_add_f32_e32 v146, v146, v147
	s_nop 1
	v_mov_b32_dpp v147, v146 quad_perm:[1,0,3,2] row_mask:0xf bank_mask:0xf
	s_mov_b32 s0, 0xf7dff200
	s_mov_b32 s1, -1
	v_lshl_add_u64 v[152:153], v[164:165], 0, s[0:1]
	s_mov_b32 s0, 0xf7dff400
	s_waitcnt lgkmcnt(0)
	v_add_f32_e32 v146, v146, v147
	s_nop 1
	v_mov_b32_dpp v147, v146 quad_perm:[2,3,0,1] row_mask:0xf bank_mask:0xf
	s_mov_b32 s1, -1
	v_lshl_add_u64 v[154:155], v[164:165], 0, s[0:1]
	s_mov_b32 s0, 0xf7dff600
	s_mov_b32 s1, -1
	s_waitcnt lgkmcnt(0)
	v_add_f32_e32 v146, v146, v147
	s_nop 1
	v_mov_b32_dpp v147, v146 row_half_mirror row_mask:0xf bank_mask:0xf
	v_lshl_add_u64 v[156:157], v[164:165], 0, s[0:1]
	s_mov_b32 s0, 0xf7dff800
	s_mov_b32 s1, -1
	v_lshl_add_u64 v[158:159], v[164:165], 0, s[0:1]
	s_waitcnt lgkmcnt(0)
	v_add_f32_e32 v146, v146, v147
	s_nop 1
	v_mov_b32_dpp v147, v146 row_mirror row_mask:0xf bank_mask:0xf
	s_mov_b32 s0, 0xf7dffa00
	s_mov_b32 s1, -1
	v_lshl_add_u64 v[160:161], v[164:165], 0, s[0:1]
	s_mov_b32 s0, 0x800000
	s_waitcnt lgkmcnt(0)
	v_add_f32_e32 v146, v146, v147
	v_mov_b32_e32 v147, v146
	s_nop 1
	v_permlane16_swap_b32_e32 v146, v147
	s_waitcnt lgkmcnt(0)
	v_add_f32_e32 v146, v146, v147
	v_mov_b32_e32 v147, v146
	s_nop 1
	v_permlane32_swap_b32_e32 v146, v147
	v_add_f32_e32 v146, v146, v147
	v_fmac_f32_e32 v187, 0xba000000, v146
	v_fmac_f32_e32 v189, 0xba000000, v146
	v_fmamk_f32 v186, v146, 0xba000000, v186
	v_fmamk_f32 v188, v146, 0xba000000, v188
	v_mul_f32_e32 v147, v189, v189
	v_mul_f32_e32 v148, v187, v187
	v_fmac_f32_e32 v147, v188, v188
	v_fmac_f32_e32 v148, v186, v186
	v_fmac_f32_e32 v179, 0xba000000, v146
	v_fmac_f32_e32 v183, 0xba000000, v146
	v_add_f32_e32 v147, v147, v148
	v_fmamk_f32 v178, v146, 0xba000000, v178
	v_fmamk_f32 v182, v146, 0xba000000, v182
	v_mul_f32_e32 v148, v183, v183
	v_mul_f32_e32 v149, v179, v179
	v_fmac_f32_e32 v148, v182, v182
	v_fmac_f32_e32 v149, v178, v178
	v_add_f32_e32 v148, v148, v149
	v_fmac_f32_e32 v171, 0xba000000, v146
	v_fmac_f32_e32 v173, 0xba000000, v146
	v_add_f32_e32 v147, v147, v148
	v_fmamk_f32 v170, v146, 0xba000000, v170
	v_fmamk_f32 v172, v146, 0xba000000, v172
	v_mul_f32_e32 v148, v173, v173
	v_mul_f32_e32 v149, v171, v171
	v_fmac_f32_e32 v148, v172, v172
	v_fmac_f32_e32 v149, v170, v170
	v_add_f32_e32 v148, v148, v149
	v_fmac_f32_e32 v167, 0xba000000, v146
	v_fmac_f32_e32 v169, 0xba000000, v146
	v_add_f32_e32 v147, v147, v148
	v_fmamk_f32 v166, v146, 0xba000000, v166
	v_fmamk_f32 v168, v146, 0xba000000, v168
	v_mul_f32_e32 v148, v169, v169
	v_mul_f32_e32 v149, v167, v167
	v_fmac_f32_e32 v148, v168, v168
	v_fmac_f32_e32 v149, v166, v166
	v_add_f32_e32 v148, v148, v149
	v_fmac_f32_e32 v143, 0xba000000, v146
	v_fmac_f32_e32 v145, 0xba000000, v146
	v_add_f32_e32 v147, v147, v148
	v_fmamk_f32 v142, v146, 0xba000000, v142
	v_fmamk_f32 v144, v146, 0xba000000, v144
	v_mul_f32_e32 v148, v145, v145
	v_mul_f32_e32 v149, v143, v143
	v_fmac_f32_e32 v148, v144, v144
	v_fmac_f32_e32 v149, v142, v142
	v_add_f32_e32 v148, v148, v149
	v_fmac_f32_e32 v139, 0xba000000, v146
	v_fmac_f32_e32 v141, 0xba000000, v146
	v_add_f32_e32 v147, v147, v148
	v_fmamk_f32 v138, v146, 0xba000000, v138
	v_fmamk_f32 v140, v146, 0xba000000, v140
	v_mul_f32_e32 v148, v141, v141
	v_mul_f32_e32 v149, v139, v139
	v_fmac_f32_e32 v148, v140, v140
	v_fmac_f32_e32 v149, v138, v138
	v_add_f32_e32 v148, v148, v149
	v_fmac_f32_e32 v135, 0xba000000, v146
	v_fmac_f32_e32 v137, 0xba000000, v146
	v_add_f32_e32 v147, v147, v148
	v_fmamk_f32 v134, v146, 0xba000000, v134
	v_fmamk_f32 v136, v146, 0xba000000, v136
	v_mul_f32_e32 v148, v137, v137
	v_mul_f32_e32 v149, v135, v135
	v_fmac_f32_e32 v148, v136, v136
	v_fmac_f32_e32 v149, v134, v134
	v_add_f32_e32 v148, v148, v149
	v_fmac_f32_e32 v131, 0xba000000, v146
	v_fmac_f32_e32 v133, 0xba000000, v146
	v_add_f32_e32 v147, v147, v148
	v_fmamk_f32 v130, v146, 0xba000000, v130
	v_fmamk_f32 v132, v146, 0xba000000, v132
	v_mul_f32_e32 v146, v133, v133
	v_mul_f32_e32 v148, v131, v131
	v_fmac_f32_e32 v146, v132, v132
	v_fmac_f32_e32 v148, v130, v130
	v_add_f32_e32 v146, v146, v148
	v_add_f32_e32 v146, v147, v146
	s_nop 1
	v_mov_b32_dpp v147, v146 quad_perm:[1,0,3,2] row_mask:0xf bank_mask:0xf
	s_waitcnt lgkmcnt(0)
	v_add_f32_e32 v146, v146, v147
	s_nop 1
	v_mov_b32_dpp v147, v146 quad_perm:[2,3,0,1] row_mask:0xf bank_mask:0xf
	s_waitcnt lgkmcnt(0)
	v_add_f32_e32 v146, v146, v147
	s_nop 1
	v_mov_b32_dpp v147, v146 row_half_mirror row_mask:0xf bank_mask:0xf
	s_waitcnt lgkmcnt(0)
	v_add_f32_e32 v146, v146, v147
	s_nop 1
	v_mov_b32_dpp v147, v146 row_mirror row_mask:0xf bank_mask:0xf
	s_waitcnt lgkmcnt(0)
	v_add_f32_e32 v146, v146, v147
	v_mov_b32_e32 v147, v146
	s_nop 1
	v_permlane16_swap_b32_e32 v146, v147
	s_waitcnt lgkmcnt(0)
; __device__ __forceinline__ unsigned cvt_pk_bf16(float lo, float hi) { unsigned r; asm volatile("v_cvt_pk_bf16_f32 %0, %1, %2" : "=v"(r) : "v"(lo), "v"(hi)); return r; }
; __global__ void __launch_bounds__(512, 2) hse_fwd(Params P) {
;     ...
;             const float rstd = rsqrtf(wave_sum(q) * (1.0f / DM) + EPS);
; #pragma unroll
;             for (int i = 0; i < 8; ++i) { const int c = i * 256 + lane * 4;
;                 const f32x4 y = (v[i] - mean) * rstd * gg[i] + bb[i]; *(u32x2*)(xr + c) = (u32x2){cvt_pk_bf16(y[0], y[1]), cvt_pk_bf16(y[2], y[3])};
;                 const f32x4 hh = y * (sc[i] + 1.0f) + sh[i];
;                 *(u32x2*)(hbuf + (size_t)ar * DM + c) = (u32x2){cvt_pk_bf16(hh[0], hh[1]), cvt_pk_bf16(hh[2], hh[3])}; } } }
	v_add_f32_e32 v146, v146, v147
	v_mov_b32_e32 v147, v146
	s_nop 1
	v_permlane32_swap_b32_e32 v146, v147
	v_add_f32_e32 v146, v146, v147
	v_mov_b32_e32 v147, 0x3727c5ac
	v_fmamk_f32 v146, v146, 0x3a000000, v147
	v_mul_f32_e32 v147, 0x4b800000, v146
	v_cmp_gt_f32_e32 vcc, s0, v146
	s_mov_b32 s0, 0xf7dffc00
	s_mov_b32 s1, -1
	v_cndmask_b32_e32 v146, v146, v147, vcc
	v_rsq_f32_e32 v148, v146
	v_lshl_add_u64 v[174:175], v[164:165], 0, s[0:1]
	s_mov_b32 s0, 0xf7dffe00
	s_mov_b32 s1, -1
	v_mul_f32_e32 v149, 0x45800000, v148
	v_cndmask_b32_e32 v148, v148, v149, vcc
	v_pk_mul_f32 v[176:177], v[148:149], v[188:189] op_sel_hi:[0,1]
	v_pk_mul_f32 v[180:181], v[148:149], v[186:187] op_sel_hi:[0,1]
	v_pk_fma_f32 v[180:181], v[26:27], v[180:181], v[36:37]
	v_pk_fma_f32 v[176:177], v[24:25], v[176:177], v[34:35]
	v_pk_add_f32 v[186:187], v[98:99], 1.0 op_sel_hi:[1,0]
	v_cvt_pk_bf16_f32 v184, v176, v177
	v_cvt_pk_bf16_f32 v185, v180, v181
	global_store_dwordx2 v[164:165], v[184:185], off offset:-3584
	v_pk_add_f32 v[184:185], v[100:101], 1.0 op_sel_hi:[1,0]
	v_pk_fma_f32 v[176:177], v[176:177], v[186:187], v[66:67]
	v_pk_fma_f32 v[180:181], v[180:181], v[184:185], v[68:69]
	v_cvt_pk_bf16_f32 v176, v176, v177
	v_pk_mul_f32 v[144:145], v[148:149], v[144:145] op_sel_hi:[0,1]
	v_cvt_pk_bf16_f32 v177, v180, v181
	global_store_dwordx2 v[152:153], v[176:177], off
	v_pk_mul_f32 v[152:153], v[148:149], v[182:183] op_sel_hi:[0,1]
	v_pk_mul_f32 v[176:177], v[148:149], v[178:179] op_sel_hi:[0,1]
	v_pk_fma_f32 v[176:177], v[30:31], v[176:177], v[40:41]
	v_pk_fma_f32 v[152:153], v[28:29], v[152:153], v[38:39]
	v_pk_add_f32 v[180:181], v[102:103], 1.0 op_sel_hi:[1,0]
	v_cvt_pk_bf16_f32 v178, v152, v153
	v_cvt_pk_bf16_f32 v179, v176, v177
	global_store_dwordx2 v[164:165], v[178:179], off offset:-3072
	v_pk_add_f32 v[178:179], v[104:105], 1.0 op_sel_hi:[1,0]
	v_pk_fma_f32 v[152:153], v[152:153], v[180:181], v[70:71]
	v_pk_fma_f32 v[176:177], v[176:177], v[178:179], v[72:73]
	v_cvt_pk_bf16_f32 v152, v152, v153
	v_pk_mul_f32 v[142:143], v[148:149], v[142:143] op_sel_hi:[0,1]
	v_cvt_pk_bf16_f32 v153, v176, v177
	global_store_dwordx2 v[154:155], v[152:153], off
	v_pk_mul_f32 v[152:153], v[148:149], v[172:173] op_sel_hi:[0,1]
	v_pk_mul_f32 v[154:155], v[148:149], v[170:171] op_sel_hi:[0,1]
	v_pk_fma_f32 v[154:155], v[18:19], v[154:155], v[44:45]
	v_pk_fma_f32 v[152:153], v[16:17], v[152:153], v[42:43]
	v_pk_add_f32 v[172:173], v[106:107], 1.0 op_sel_hi:[1,0]
	v_cvt_pk_bf16_f32 v170, v152, v153
	v_cvt_pk_bf16_f32 v171, v154, v155
	global_store_dwordx2 v[164:165], v[170:171], off offset:-2560
	v_pk_add_f32 v[170:171], v[108:109], 1.0 op_sel_hi:[1,0]
	v_pk_fma_f32 v[152:153], v[152:153], v[172:173], v[74:75]
	v_pk_fma_f32 v[154:155], v[154:155], v[170:171], v[76:77]
	v_cvt_pk_bf16_f32 v152, v152, v153
	v_pk_fma_f32 v[142:143], v[2:3], v[142:143], v[52:53]
	v_cvt_pk_bf16_f32 v153, v154, v155
	global_store_dwordx2 v[156:157], v[152:153], off
	v_pk_mul_f32 v[152:153], v[148:149], v[168:169] op_sel_hi:[0,1]
	v_pk_mul_f32 v[154:155], v[148:149], v[166:167] op_sel_hi:[0,1]
	v_pk_fma_f32 v[154:155], v[22:23], v[154:155], v[48:49]
	v_pk_fma_f32 v[152:153], v[20:21], v[152:153], v[46:47]
	v_pk_add_f32 v[166:167], v[110:111], 1.0 op_sel_hi:[1,0]
	v_cvt_pk_bf16_f32 v156, v152, v153
	v_cvt_pk_bf16_f32 v157, v154, v155
	global_store_dwordx2 v[164:165], v[156:157], off offset:-2048
	v_pk_add_f32 v[156:157], v[112:113], 1.0 op_sel_hi:[1,0]
	v_pk_fma_f32 v[152:153], v[152:153], v[166:167], v[78:79]
	v_pk_fma_f32 v[154:155], v[154:155], v[156:157], v[80:81]
	v_cvt_pk_bf16_f32 v152, v152, v153
	v_pk_fma_f32 v[144:145], v[0:1], v[144:145], v[50:51]
	v_cvt_pk_bf16_f32 v153, v154, v155
	global_store_dwordx2 v[158:159], v[152:153], off
	v_cvt_pk_bf16_f32 v152, v144, v145
	v_cvt_pk_bf16_f32 v153, v142, v143
	v_pk_add_f32 v[154:155], v[114:115], 1.0 op_sel_hi:[1,0]
	global_store_dwordx2 v[164:165], v[152:153], off offset:-1536
	v_pk_add_f32 v[152:153], v[116:117], 1.0 op_sel_hi:[1,0]
	v_pk_fma_f32 v[144:145], v[144:145], v[154:155], v[82:83]
	v_lshl_add_u64 v[150:151], v[164:165], 0, s[0:1]
	s_mov_b32 s0, 0xf7e00000
	v_pk_fma_f32 v[142:143], v[142:143], v[152:153], v[84:85]
	v_cvt_pk_bf16_f32 v144, v144, v145
	v_pk_mul_f32 v[140:141], v[148:149], v[140:141] op_sel_hi:[0,1]
	v_cvt_pk_bf16_f32 v145, v142, v143
	v_pk_mul_f32 v[138:139], v[148:149], v[138:139] op_sel_hi:[0,1]
	s_mov_b32 s1, -1
	global_store_dwordx2 v[160:161], v[144:145], off
	v_pk_fma_f32 v[138:139], v[14:15], v[138:139], v[56:57]
	v_pk_fma_f32 v[140:141], v[12:13], v[140:141], v[54:55]
	v_pk_add_f32 v[144:145], v[118:119], 1.0 op_sel_hi:[1,0]
	v_cvt_pk_bf16_f32 v142, v140, v141
	v_cvt_pk_bf16_f32 v143, v138, v139
	v_lshl_add_u64 v[146:147], v[164:165], 0, s[0:1]
	global_store_dwordx2 v[164:165], v[142:143], off offset:-1024
	v_pk_add_f32 v[142:143], v[120:121], 1.0 op_sel_hi:[1,0]
	v_pk_fma_f32 v[140:141], v[140:141], v[144:145], v[86:87]
	v_readlane_b32 s0, v253, 9
	v_pk_fma_f32 v[138:139], v[138:139], v[142:143], v[88:89]
	v_cvt_pk_bf16_f32 v140, v140, v141
	v_pk_mul_f32 v[136:137], v[148:149], v[136:137] op_sel_hi:[0,1]
	v_cvt_pk_bf16_f32 v141, v138, v139
	v_pk_mul_f32 v[134:135], v[148:149], v[134:135] op_sel_hi:[0,1]
	v_readlane_b32 s1, v253, 10
	global_store_dwordx2 v[174:175], v[140:141], off
	v_pk_fma_f32 v[134:135], v[10:11], v[134:135], v[60:61]
	v_pk_fma_f32 v[136:137], v[8:9], v[136:137], v[58:59]
	v_pk_add_f32 v[140:141], v[122:123], 1.0 op_sel_hi:[1,0]
	v_cvt_pk_bf16_f32 v138, v136, v137
	v_cvt_pk_bf16_f32 v139, v134, v135
	s_add_i32 s10, s10, s0
	v_readlane_b32 s0, v255, 24
	global_store_dwordx2 v[164:165], v[138:139], off offset:-512
	v_pk_add_f32 v[138:139], v[124:125], 1.0 op_sel_hi:[1,0]
	v_pk_fma_f32 v[136:137], v[136:137], v[140:141], v[90:91]
	v_readlane_b32 s1, v255, 25
	s_add_u32 s4, s4, s0
	v_pk_fma_f32 v[134:135], v[134:135], v[138:139], v[92:93]
	v_cvt_pk_bf16_f32 v136, v136, v137
	v_pk_mul_f32 v[132:133], v[148:149], v[132:133] op_sel_hi:[0,1]
	v_cvt_pk_bf16_f32 v137, v134, v135
	v_pk_mul_f32 v[130:131], v[148:149], v[130:131] op_sel_hi:[0,1]
	s_addc_u32 s5, s5, s1
	v_readlane_b32 s0, v255, 22
	global_store_dwordx2 v[150:151], v[136:137], off
	v_pk_fma_f32 v[130:131], v[6:7], v[130:131], v[64:65]
	v_pk_fma_f32 v[132:133], v[4:5], v[132:133], v[62:63]
	v_pk_add_f32 v[136:137], v[126:127], 1.0 op_sel_hi:[1,0]
	v_cvt_pk_bf16_f32 v134, v132, v133
	v_cvt_pk_bf16_f32 v135, v130, v131
	v_readlane_b32 s1, v255, 23
	global_store_dwordx2 v[164:165], v[134:135], off
	v_pk_add_f32 v[134:135], v[128:129], 1.0 op_sel_hi:[1,0]
	v_pk_fma_f32 v[132:133], v[132:133], v[136:137], v[94:95]
	s_cmp_gt_i32 s10, 0x81ff
	v_lshl_add_u64 v[164:165], v[164:165], 0, s[0:1]
	v_pk_fma_f32 v[130:131], v[130:131], v[134:135], v[96:97]
	v_cvt_pk_bf16_f32 v132, v132, v133
	s_nop 0
	v_cvt_pk_bf16_f32 v133, v130, v131
	global_store_dwordx2 v[146:147], v[132:133], off
	s_cbranch_scc1 .LBB0_5432

; __device__ __forceinline__ float bf_lo(unsigned w) { return __uint_as_float(w << 16); }
; __device__ __forceinline__ float bf_hi(unsigned w) { return __uint_as_float(w & 0xffff0000u); }
; __global__ void __launch_bounds__(512, 2) hse_fwd(Params P) {
;     ...
;           for (int ar = bid * 8 + wave; ar < MX; ar += G * 8) { bf16_t* xr = xbuf + (size_t)ar * DM; float* yo = out + O_Y + (size_t)ar * DM; f32x4 v[8]; float s = 0.f; const bf16_t* vb = hbuf + (size_t)ar * DM;
;             const int st = row_stream(ar); const float* a = adan + (size_t)st * NADA;
; #pragma unroll
;             for (int i = 0; i < 8; ++i) { const u32x2 xw = *(const u32x2*)(xr + i * 256 + lane * 4), w = *(const u32x2*)(vb + i * 256 + lane * 4);
;                 v[i] = (f32x4){bf_lo(xw.x), bf_hi(xw.x), bf_lo(xw.y), bf_hi(xw.y)} * ALPHA + (f32x4){bf_lo(w.x), bf_hi(w.x), bf_lo(w.y), bf_hi(w.y)}; s += (v[i][0] + v[i][1]) + (v[i][2] + v[i][3]); }
;             if (l == 0 && st != cst) { cst = st;
; #pragma unroll
;                 for (int i = 0; i < 8; ++i) { const int c = i * 256 + lane * 4; sh[i] = *(const f32x4*)(a + c); sc[i] = *(const f32x4*)(a + DM + c); } }
;             const float mean = wave_sum(s) * (1.0f / DM); float q = 0.f;
.LBB0_5749:
	s_waitcnt vmcnt(15)
	v_lshlrev_b32_e32 v166, 16, v130
	v_and_b32_e32 v167, 0xffff0000, v130
	v_lshlrev_b32_e32 v130, 16, v131
	v_and_b32_e32 v131, 0xffff0000, v131
	s_waitcnt vmcnt(11)
	v_lshlrev_b32_e32 v178, 16, v132
	v_and_b32_e32 v179, 0xffff0000, v132
	v_lshlrev_b32_e32 v132, 16, v133
	v_and_b32_e32 v133, 0xffff0000, v133
	s_mov_b32 s0, 0x3fb504f3
	v_pk_fma_f32 v[130:131], v[130:131], s[0:1], v[132:133] op_sel_hi:[1,0,1]
	v_pk_fma_f32 v[132:133], v[166:167], s[0:1], v[178:179] op_sel_hi:[1,0,1]
	v_add_f32_e32 v167, v130, v131
	v_add_f32_e32 v166, v132, v133
	v_add_f32_e32 v166, v166, v167
	v_add_f32_e32 v180, 0, v166
	v_lshlrev_b32_e32 v166, 16, v162
	v_and_b32_e32 v167, 0xffff0000, v162
	v_lshlrev_b32_e32 v162, 16, v163
	v_and_b32_e32 v163, 0xffff0000, v163
	s_waitcnt vmcnt(10)
	v_lshlrev_b32_e32 v178, 16, v164
	v_and_b32_e32 v179, 0xffff0000, v164
	v_lshlrev_b32_e32 v164, 16, v165
	v_and_b32_e32 v165, 0xffff0000, v165
	v_pk_fma_f32 v[164:165], v[162:163], s[0:1], v[164:165] op_sel_hi:[1,0,1]
	v_pk_fma_f32 v[166:167], v[166:167], s[0:1], v[178:179] op_sel_hi:[1,0,1]
	v_add_f32_e32 v163, v164, v165
	v_add_f32_e32 v162, v166, v167
	v_add_f32_e32 v162, v162, v163
	v_add_f32_e32 v180, v180, v162
	v_lshlrev_b32_e32 v162, 16, v158
	v_and_b32_e32 v163, 0xffff0000, v158
	v_lshlrev_b32_e32 v158, 16, v159
	v_and_b32_e32 v159, 0xffff0000, v159
	s_waitcnt vmcnt(9)
	v_lshlrev_b32_e32 v178, 16, v160
	v_and_b32_e32 v179, 0xffff0000, v160
	v_lshlrev_b32_e32 v160, 16, v161
	v_and_b32_e32 v161, 0xffff0000, v161
	v_pk_fma_f32 v[160:161], v[158:159], s[0:1], v[160:161] op_sel_hi:[1,0,1]
	v_pk_fma_f32 v[162:163], v[162:163], s[0:1], v[178:179] op_sel_hi:[1,0,1]
	v_add_f32_e32 v159, v160, v161
	v_add_f32_e32 v158, v162, v163
	v_add_f32_e32 v158, v158, v159
	v_add_f32_e32 v180, v180, v158
	v_lshlrev_b32_e32 v158, 16, v154
	v_and_b32_e32 v159, 0xffff0000, v154
	v_lshlrev_b32_e32 v154, 16, v155
	v_and_b32_e32 v155, 0xffff0000, v155
	s_waitcnt vmcnt(8)
	v_lshlrev_b32_e32 v178, 16, v156
	v_and_b32_e32 v179, 0xffff0000, v156
	v_lshlrev_b32_e32 v156, 16, v157
	v_and_b32_e32 v157, 0xffff0000, v157
	v_pk_fma_f32 v[156:157], v[154:155], s[0:1], v[156:157] op_sel_hi:[1,0,1]
	v_pk_fma_f32 v[158:159], v[158:159], s[0:1], v[178:179] op_sel_hi:[1,0,1]
	v_add_f32_e32 v155, v156, v157
	v_add_f32_e32 v154, v158, v159
	v_add_f32_e32 v154, v154, v155
	v_add_f32_e32 v180, v180, v154
	s_waitcnt vmcnt(7)
	v_lshlrev_b32_e32 v154, 16, v150
	v_and_b32_e32 v155, 0xffff0000, v150
	v_lshlrev_b32_e32 v150, 16, v151
	v_and_b32_e32 v151, 0xffff0000, v151
	s_waitcnt vmcnt(3)
	v_lshlrev_b32_e32 v178, 16, v152
	v_and_b32_e32 v179, 0xffff0000, v152
	v_lshlrev_b32_e32 v152, 16, v153
	v_and_b32_e32 v153, 0xffff0000, v153
	v_pk_fma_f32 v[150:151], v[150:151], s[0:1], v[152:153] op_sel_hi:[1,0,1]
	v_pk_fma_f32 v[152:153], v[154:155], s[0:1], v[178:179] op_sel_hi:[1,0,1]
	v_add_f32_e32 v155, v150, v151
	v_add_f32_e32 v154, v152, v153
	v_add_f32_e32 v154, v154, v155
	v_add_f32_e32 v180, v180, v154
	v_lshlrev_b32_e32 v154, 16, v146
	v_and_b32_e32 v155, 0xffff0000, v146
	v_lshlrev_b32_e32 v146, 16, v147
	v_and_b32_e32 v147, 0xffff0000, v147
	s_waitcnt vmcnt(2)
	v_lshlrev_b32_e32 v178, 16, v148
	v_and_b32_e32 v179, 0xffff0000, v148
	v_lshlrev_b32_e32 v148, 16, v149
	v_and_b32_e32 v149, 0xffff0000, v149
	v_pk_fma_f32 v[146:147], v[146:147], s[0:1], v[148:149] op_sel_hi:[1,0,1]
	v_pk_fma_f32 v[148:149], v[154:155], s[0:1], v[178:179] op_sel_hi:[1,0,1]
	v_add_f32_e32 v155, v146, v147
	v_add_f32_e32 v154, v148, v149
	v_add_f32_e32 v154, v154, v155
	v_add_f32_e32 v180, v180, v154
	v_lshlrev_b32_e32 v154, 16, v142
	v_and_b32_e32 v155, 0xffff0000, v142
	v_lshlrev_b32_e32 v142, 16, v143
	v_and_b32_e32 v143, 0xffff0000, v143
	s_waitcnt vmcnt(1)
	v_lshlrev_b32_e32 v178, 16, v144
	v_and_b32_e32 v179, 0xffff0000, v144
	v_lshlrev_b32_e32 v144, 16, v145
	v_and_b32_e32 v145, 0xffff0000, v145
	v_pk_fma_f32 v[142:143], v[142:143], s[0:1], v[144:145] op_sel_hi:[1,0,1]
	v_pk_fma_f32 v[144:145], v[154:155], s[0:1], v[178:179] op_sel_hi:[1,0,1]
	v_add_f32_e32 v155, v142, v143
	v_add_f32_e32 v154, v144, v145
	v_add_f32_e32 v154, v154, v155
	v_add_f32_e32 v180, v180, v154
	v_lshlrev_b32_e32 v154, 16, v138
	v_and_b32_e32 v155, 0xffff0000, v138
	v_lshlrev_b32_e32 v138, 16, v139
	v_and_b32_e32 v139, 0xffff0000, v139
	s_waitcnt vmcnt(0)
	v_lshlrev_b32_e32 v178, 16, v140
	v_and_b32_e32 v179, 0xffff0000, v140
	v_lshlrev_b32_e32 v140, 16, v141
	v_and_b32_e32 v141, 0xffff0000, v141
	v_pk_fma_f32 v[138:139], v[138:139], s[0:1], v[140:141] op_sel_hi:[1,0,1]
	v_pk_fma_f32 v[140:141], v[154:155], s[0:1], v[178:179] op_sel_hi:[1,0,1]
	v_add_f32_e32 v155, v138, v139
	v_add_f32_e32 v154, v140, v141
	v_add_f32_e32 v154, v154, v155
	v_add_f32_e32 v154, v180, v154
	s_nop 1
	v_mov_b32_dpp v155, v154 quad_perm:[1,0,3,2] row_mask:0xf bank_mask:0xf
	s_mov_b32 s0, 0x800000
	v_readlane_b32 s4, v255, 30
	v_readlane_b32 s5, v255, 31
	s_waitcnt lgkmcnt(0)
; __device__ __forceinline__ unsigned cvt_pk_bf16(float lo, float hi) { unsigned r; asm volatile("v_cvt_pk_bf16_f32 %0, %1, %2" : "=v"(r) : "v"(lo), "v"(hi)); return r; }
; __device__ __forceinline__ float wave_sum(float v) {
;     v += __int_as_float(__builtin_amdgcn_ds_swizzle(__float_as_int(v), 0x041F));
;     v += __int_as_float(__builtin_amdgcn_ds_swizzle(__float_as_int(v), 0x081F));
;     v += __int_as_float(__builtin_amdgcn_ds_swizzle(__float_as_int(v), 0x101F));
;     v += __int_as_float(__builtin_amdgcn_ds_swizzle(__float_as_int(v), 0x201F));
;     v += __int_as_float(__builtin_amdgcn_ds_swizzle(__float_as_int(v), 0x401F));
;     auto rr = __builtin_amdgcn_permlane32_swap(__float_as_uint(v), __float_as_uint(v), false, false);
;     return __uint_as_float(rr[0]) + __uint_as_float(rr[1]);
; __global__ void __launch_bounds__(512, 2) hse_fwd(Params P) {
;     ...
;             const float mean = wave_sum(s) * (1.0f / DM); float q = 0.f;
; #pragma unroll
;             for (int i = 0; i < 8; ++i) { const f32x4 d = v[i] - mean; q += (d[0] * d[0] + d[1] * d[1]) + (d[2] * d[2] + d[3] * d[3]); }
;             const float rstd = rsqrtf(wave_sum(q) * (1.0f / DM) + EPS);
; #pragma unroll
;             for (int i = 0; i < 8; ++i) { const int c = i * 256 + lane * 4;
;                 const f32x4 y = (v[i] - mean) * rstd * gg[i] + bb[i];
;                 if (l == 0) { *(u32x2*)(xr + c) = (u32x2){cvt_pk_bf16(y[0], y[1]), cvt_pk_bf16(y[2], y[3])};
;                     const f32x4 hh = y * (sc[i] + 1.0f) + sh[i];
;                     *(u32x2*)(hbuf + (size_t)ar * DM + c) = (u32x2){cvt_pk_bf16(hh[0], hh[1]), cvt_pk_bf16(hh[2], hh[3])}; }
;                 else *(f32x4*)(yo + c) = y; } }
	v_add_f32_e32 v154, v154, v155
	s_nop 1
	v_mov_b32_dpp v155, v154 quad_perm:[2,3,0,1] row_mask:0xf bank_mask:0xf
	s_waitcnt lgkmcnt(0)
	v_add_f32_e32 v154, v154, v155
	s_nop 1
	v_mov_b32_dpp v155, v154 row_half_mirror row_mask:0xf bank_mask:0xf
	s_waitcnt lgkmcnt(0)
	v_add_f32_e32 v154, v154, v155
	s_nop 1
	v_mov_b32_dpp v155, v154 row_mirror row_mask:0xf bank_mask:0xf
	s_waitcnt lgkmcnt(0)
	v_add_f32_e32 v154, v154, v155
	v_mov_b32_e32 v155, v154
	s_nop 1
	v_permlane16_swap_b32_e32 v154, v155
	s_waitcnt lgkmcnt(0)
	v_add_f32_e32 v154, v154, v155
	v_mov_b32_e32 v155, v154
	s_nop 1
	v_permlane32_swap_b32_e32 v154, v155
	v_add_f32_e32 v154, v154, v155
	v_fmac_f32_e32 v131, 0xba000000, v154
	v_fmac_f32_e32 v133, 0xba000000, v154
	v_fmamk_f32 v130, v154, 0xba000000, v130
	v_fmamk_f32 v132, v154, 0xba000000, v132
	v_mul_f32_e32 v155, v133, v133
	v_mul_f32_e32 v178, v131, v131
	v_fmac_f32_e32 v155, v132, v132
	v_fmac_f32_e32 v178, v130, v130
	v_fmamk_f32 v165, v154, 0xba000000, v165
	v_fmamk_f32 v167, v154, 0xba000000, v167
	v_add_f32_e32 v155, v155, v178
	v_fmac_f32_e32 v164, 0xba000000, v154
	v_fmac_f32_e32 v166, 0xba000000, v154
	v_mul_f32_e32 v178, v167, v167
	v_mul_f32_e32 v179, v165, v165
	v_fmac_f32_e32 v178, v166, v166
	v_fmac_f32_e32 v179, v164, v164
	v_add_f32_e32 v178, v178, v179
	v_fmamk_f32 v161, v154, 0xba000000, v161
	v_fmamk_f32 v163, v154, 0xba000000, v163
	v_add_f32_e32 v155, v155, v178
	v_fmac_f32_e32 v160, 0xba000000, v154
	v_fmac_f32_e32 v162, 0xba000000, v154
	v_mul_f32_e32 v178, v163, v163
	v_mul_f32_e32 v179, v161, v161
	v_fmac_f32_e32 v178, v162, v162
	v_fmac_f32_e32 v179, v160, v160
	v_add_f32_e32 v178, v178, v179
	v_fmamk_f32 v157, v154, 0xba000000, v157
	v_fmamk_f32 v159, v154, 0xba000000, v159
	v_add_f32_e32 v155, v155, v178
	v_fmac_f32_e32 v156, 0xba000000, v154
	v_fmac_f32_e32 v158, 0xba000000, v154
	v_mul_f32_e32 v178, v159, v159
	v_mul_f32_e32 v179, v157, v157
	v_fmac_f32_e32 v178, v158, v158
	v_fmac_f32_e32 v179, v156, v156
	v_add_f32_e32 v178, v178, v179
	v_fmamk_f32 v151, v154, 0xba000000, v151
	v_fmamk_f32 v153, v154, 0xba000000, v153
	v_add_f32_e32 v155, v155, v178
	v_fmac_f32_e32 v150, 0xba000000, v154
	v_fmac_f32_e32 v152, 0xba000000, v154
	v_mul_f32_e32 v178, v153, v153
	v_mul_f32_e32 v179, v151, v151
	v_fmac_f32_e32 v178, v152, v152
	v_fmac_f32_e32 v179, v150, v150
	v_add_f32_e32 v178, v178, v179
	v_fmamk_f32 v147, v154, 0xba000000, v147
	v_fmamk_f32 v149, v154, 0xba000000, v149
	v_add_f32_e32 v155, v155, v178
	v_fmac_f32_e32 v146, 0xba000000, v154
	v_fmac_f32_e32 v148, 0xba000000, v154
	v_mul_f32_e32 v178, v149, v149
	v_mul_f32_e32 v179, v147, v147
	v_fmac_f32_e32 v178, v148, v148
	v_fmac_f32_e32 v179, v146, v146
	v_add_f32_e32 v178, v178, v179
	v_fmamk_f32 v143, v154, 0xba000000, v143
	v_fmamk_f32 v145, v154, 0xba000000, v145
	v_add_f32_e32 v155, v155, v178
	v_fmac_f32_e32 v142, 0xba000000, v154
	v_fmac_f32_e32 v144, 0xba000000, v154
	v_mul_f32_e32 v178, v145, v145
	v_mul_f32_e32 v179, v143, v143
	v_fmac_f32_e32 v178, v144, v144
	v_fmac_f32_e32 v179, v142, v142
	v_add_f32_e32 v178, v178, v179
	v_fmamk_f32 v139, v154, 0xba000000, v139
	v_fmamk_f32 v141, v154, 0xba000000, v141
	v_add_f32_e32 v155, v155, v178
	v_fmac_f32_e32 v138, 0xba000000, v154
	v_fmac_f32_e32 v140, 0xba000000, v154
	v_mul_f32_e32 v154, v141, v141
	v_mul_f32_e32 v178, v139, v139
	v_fmac_f32_e32 v154, v140, v140
	v_fmac_f32_e32 v178, v138, v138
	v_add_f32_e32 v154, v154, v178
	v_add_f32_e32 v154, v155, v154
	s_nop 1
	v_mov_b32_dpp v155, v154 quad_perm:[1,0,3,2] row_mask:0xf bank_mask:0xf
	s_waitcnt lgkmcnt(0)
	v_add_f32_e32 v154, v154, v155
	s_nop 1
	v_mov_b32_dpp v155, v154 quad_perm:[2,3,0,1] row_mask:0xf bank_mask:0xf
	s_waitcnt lgkmcnt(0)
	v_add_f32_e32 v154, v154, v155
	s_nop 1
	v_mov_b32_dpp v155, v154 row_half_mirror row_mask:0xf bank_mask:0xf
	s_waitcnt lgkmcnt(0)
	v_add_f32_e32 v154, v154, v155
	s_nop 1
	v_mov_b32_dpp v155, v154 row_mirror row_mask:0xf bank_mask:0xf
	s_waitcnt lgkmcnt(0)
	v_add_f32_e32 v154, v154, v155
	v_mov_b32_e32 v155, v154
	s_nop 1
	v_permlane16_swap_b32_e32 v154, v155
	s_waitcnt lgkmcnt(0)
	v_add_f32_e32 v154, v154, v155
	v_mov_b32_e32 v155, v154
	s_nop 1
	v_permlane32_swap_b32_e32 v154, v155
	v_add_f32_e32 v154, v154, v155
	v_mov_b32_e32 v155, 0x3727c5ac
	v_fmamk_f32 v154, v154, 0x3a000000, v155
	v_mul_f32_e32 v155, 0x4b800000, v154
	v_cmp_gt_f32_e32 vcc, s0, v154
	s_mov_b64 s[0:1], -1
	s_nop 0
	v_cndmask_b32_e32 v154, v154, v155, vcc
	v_rsq_f32_e32 v154, v154
	s_nop 0
	v_mul_f32_e32 v155, 0x45800000, v154
	v_cndmask_b32_e32 v154, v154, v155, vcc
	v_pk_mul_f32 v[178:179], v[154:155], v[132:133] op_sel_hi:[0,1]
	v_pk_mul_f32 v[130:131], v[154:155], v[130:131] op_sel_hi:[0,1]
	v_pk_fma_f32 v[132:133], v[2:3], v[130:131], v[6:7]
	v_pk_fma_f32 v[130:131], v[0:1], v[178:179], v[4:5]
	s_and_b64 vcc, exec, s[4:5]
	s_cbranch_vccz .LBB0_5751
	v_add_co_u32_e32 v178, vcc, 0xfffff000, v136
	s_mov_b64 s[0:1], 0
	s_nop 0
	v_addc_co_u32_e32 v179, vcc, -1, v137, vcc
	global_store_dwordx4 v[178:179], v[130:133], off offset:-3072
